# v61 + prologue W_in transpose item: all 16 tile loads in flight before the first wait (hipcc waited after 2 loads: 2 round trips per item)
# speedup vs baseline: 1.0111x; 1.0111x over previous
; #define GAS __attribute__((address_space(1)))
; __device__ __forceinline__ unsigned cvt_pk_bf16(float lo, float hi) { const f32x2 v = {lo, hi}; return __builtin_bit_cast(unsigned, __builtin_convertvector(v, bf16n2)); }
;     __device__ __forceinline__ int lane_() const { return lane_id(); }
; #define F_w_in F.in(8)
; __device__ __forceinline__ void p0_transpose_item(const GAS float* W, int K, int N, GAS bf16* WT, int item, int lane) {
;     const int nblk = N / 64, kb = item / nblk, nb = item - kb * nblk, r = lane >> 4, c4 = lane & 15;
;     const GAS float* src = W + (size_t)(64 * kb + 16 * r) * N + 64 * nb + 4 * c4;
;     f32x4 v[16];
; #pragma unroll
;     for (int i = 0; i < 16; ++i) v[i] = __builtin_nontemporal_load((const GAS f32x4*)(src + (size_t)i * N));
;     GAS bf16* dst = WT + (size_t)(64 * nb + 4 * c4) * K + 64 * kb + 16 * r;
; #pragma unroll
;     for (int j = 0; j < 4; ++j) { v4u a, b;
;         a.x = cvt_pk_bf16(v[0][j], v[1][j]); a.y = cvt_pk_bf16(v[2][j], v[3][j]); a.z = cvt_pk_bf16(v[4][j], v[5][j]); a.w = cvt_pk_bf16(v[6][j], v[7][j]);
;         b.x = cvt_pk_bf16(v[8][j], v[9][j]); b.y = cvt_pk_bf16(v[10][j], v[11][j]); b.z = cvt_pk_bf16(v[12][j], v[13][j]); b.w = cvt_pk_bf16(v[14][j], v[15][j]);
;         *(GAS v4u*)(dst + (size_t)j * K) = a; *(GAS v4u*)(dst + (size_t)j * K + 8) = b; }
; }
; __device__ __forceinline__ void phase_prologue(Frame& F) {
;     ...
;     for (int it = gw; it < NITEMS; it += NGW) {
;         int r = it;
;         if (r < 2 * I_IN) { const int l = r / I_IN; p0_transpose_item(F_w_in + (size_t)l * D * NPROJ, D, NPROJ, win_t + (size_t)l * NPROJ * D, r % I_IN, F.lane_()); continue; } r -= 2 * I_IN;
.LBB0_27:
	s_andn2_b64 vcc, exec, s[10:11]
	s_cbranch_vccnz .LBB0_16
	v_mov_b32_e32 v0, s44
	ds_read_b64 v[2:3], v0
	s_mul_hi_i32 s8, s59, 0x4ec4ec4f
	s_lshr_b32 s10, s8, 31
	s_ashr_i32 s8, s8, 10
	s_add_i32 s8, s8, s10
	s_waitcnt lgkmcnt(0)
	v_readfirstlane_b32 s11, v2
	s_mul_i32 s13, s8, 0x3400000
	v_readfirstlane_b32 s10, v3
	s_mul_hi_i32 s12, s8, 0x3400000
	s_add_u32 s14, s11, s13
	s_addc_u32 s15, s10, s12
	s_mul_i32 s10, s8, 0x1a00000
	s_mul_hi_i32 s11, s8, 0x1a00000
	s_add_u32 s10, s1, s10
	s_mulk_i32 s8, 0xf300
	s_addc_u32 s11, s7, s11
	s_add_i32 s8, s59, s8
	v_mov_b32_e32 v0, 0
	s_mul_i32 s12, s8, 0x4ec5
	v_mbcnt_lo_u32_b32 v0, -1, v0
	s_lshr_b32 s13, s12, 31
	s_ashr_i32 s12, s12, 22
	v_mbcnt_hi_u32_b32 v0, -1, v0
	s_add_i32 s12, s12, s13
	s_mul_i32 s13, s12, 0xffffff30
	s_lshl_b32 s12, s12, 6
	v_and_b32_e32 v68, -16, v0
	v_add_u32_e32 v4, s12, v68
	v_mov_b64_e32 v[2:3], s[14:15]
	s_add_i32 s8, s8, s13
	v_mad_i64_i32 v[2:3], s[14:15], v4, s40, v[2:3]
	s_lshl_b32 s14, s8, 6
	v_lshlrev_b32_e32 v0, 2, v0
	s_ashr_i32 s15, s14, 31
	v_and_b32_e32 v69, 60, v0
	v_lshl_add_u64 v[2:3], s[14:15], 2, v[2:3]
	v_lshlrev_b32_e32 v0, 2, v69
	v_lshl_add_u64 v[42:43], v[2:3], 0, v[0:1]
	v_add_co_u32_e32 v6, vcc, s40, v42
	s_ashr_i32 s13, s12, 31
	s_nop 0
	v_addc_co_u32_e32 v7, vcc, 0, v43, vcc
	v_add_co_u32_e32 v10, vcc, s45, v42
	global_load_dwordx4 v[2:5], v[42:43], off nt
	s_nop 0
	global_load_dwordx4 v[6:9], v[6:7], off nt
	v_addc_co_u32_e32 v11, vcc, 0, v43, vcc
	v_add_co_u32_e32 v14, vcc, s46, v42
	v_addc_co_u32_e32 v15, vcc, 0, v43, vcc
	v_add_co_u32_e32 v18, vcc, s47, v42
	global_load_dwordx4 v[10:13], v[10:11], off nt
	s_nop 0
	global_load_dwordx4 v[14:17], v[14:15], off nt
	v_addc_co_u32_e32 v19, vcc, 0, v43, vcc
	v_add_co_u32_e32 v22, vcc, s48, v42
	v_or_b32_e32 v80, s14, v69
	s_nop 0
	v_addc_co_u32_e32 v23, vcc, 0, v43, vcc
	v_add_co_u32_e32 v26, vcc, s49, v42
	global_load_dwordx4 v[18:21], v[18:19], off nt
	s_nop 0
	global_load_dwordx4 v[22:25], v[22:23], off nt
	v_addc_co_u32_e32 v27, vcc, 0, v43, vcc
	v_add_co_u32_e32 v30, vcc, s50, v42
	s_nop 0
	v_addc_co_u32_e32 v31, vcc, 0, v43, vcc
	v_add_co_u32_e32 v34, vcc, s51, v42
	global_load_dwordx4 v[26:29], v[26:27], off nt
	s_nop 0
	global_load_dwordx4 v[30:33], v[30:31], off nt
	v_addc_co_u32_e32 v35, vcc, 0, v43, vcc
	v_add_co_u32_e32 v38, vcc, s52, v42
	v_ashrrev_i32_e32 v81, 31, v80
	s_nop 0
	v_addc_co_u32_e32 v39, vcc, 0, v43, vcc
	v_add_co_u32_e32 v44, vcc, s53, v42
	global_load_dwordx4 v[34:37], v[34:35], off nt
	s_nop 0
	global_load_dwordx4 v[38:41], v[38:39], off nt
	v_addc_co_u32_e32 v45, vcc, 0, v43, vcc
	v_add_co_u32_e32 v46, vcc, s54, v42
	v_lshlrev_b64 v[80:81], 11, v[80:81]
	s_nop 0
	v_addc_co_u32_e32 v47, vcc, 0, v43, vcc
	v_add_co_u32_e32 v50, vcc, s55, v42
	v_lshl_add_u64 v[80:81], s[10:11], 0, v[80:81]
	s_nop 0
	v_addc_co_u32_e32 v51, vcc, 0, v43, vcc
	v_add_co_u32_e32 v54, vcc, s56, v42
	v_lshl_add_u64 v[80:81], s[12:13], 1, v[80:81]
	s_nop 0
	v_addc_co_u32_e32 v55, vcc, 0, v43, vcc
	v_add_co_u32_e32 v58, vcc, s57, v42
	v_ashrrev_i32_e32 v69, 31, v68
	s_nop 0
	v_addc_co_u32_e32 v59, vcc, 0, v43, vcc
	v_add_co_u32_e32 v62, vcc, s58, v42
	s_nop 0
	v_addc_co_u32_e32 v63, vcc, 0, v43, vcc
	global_load_dwordx4 v[42:45], v[44:45], off nt
	s_nop 0
	global_load_dwordx4 v[46:49], v[46:47], off nt
	s_nop 0
	global_load_dwordx4 v[50:53], v[50:51], off nt
	s_nop 0
	global_load_dwordx4 v[54:57], v[54:55], off nt
	s_nop 0
	global_load_dwordx4 v[58:61], v[58:59], off nt
	s_nop 0
	global_load_dwordx4 v[62:65], v[62:63], off nt
	s_waitcnt vmcnt(14)
	v_cvt_pk_bf16_f32 v66, v4, v8
	v_cvt_pk_bf16_f32 v70, v5, v9
	v_cvt_pk_bf16_f32 v2, v2, v6
	v_cvt_pk_bf16_f32 v6, v3, v7
	s_waitcnt vmcnt(12)
	v_cvt_pk_bf16_f32 v3, v10, v14
	v_cvt_pk_bf16_f32 v7, v11, v15
	v_lshl_add_u64 v[10:11], v[68:69], 1, v[80:81]
	v_cvt_pk_bf16_f32 v67, v12, v16
	v_cvt_pk_bf16_f32 v71, v13, v17
	s_waitcnt vmcnt(10)
	v_cvt_pk_bf16_f32 v4, v18, v22
	v_cvt_pk_bf16_f32 v8, v19, v23
	v_cvt_pk_bf16_f32 v68, v20, v24
	v_cvt_pk_bf16_f32 v72, v21, v25
	s_waitcnt vmcnt(8)
	v_cvt_pk_bf16_f32 v5, v26, v30
	global_store_dwordx4 v[10:11], v[2:5], off
	v_cvt_pk_bf16_f32 v9, v27, v31
	global_store_dwordx4 v[10:11], v[6:9], off offset:2048
	v_cvt_pk_bf16_f32 v69, v28, v32
	v_cvt_pk_bf16_f32 v73, v29, v33
	v_add_co_u32_e32 v6, vcc, s27, v10
	s_waitcnt vmcnt(8)
	v_cvt_pk_bf16_f32 v2, v34, v38
	v_addc_co_u32_e32 v7, vcc, 0, v11, vcc
	global_store_dwordx4 v[6:7], v[66:69], off
	s_waitcnt vmcnt(7)
	v_cvt_pk_bf16_f32 v3, v42, v46
	s_waitcnt vmcnt(5)
	v_cvt_pk_bf16_f32 v4, v50, v54
	s_waitcnt vmcnt(3)
	v_cvt_pk_bf16_f32 v5, v58, v62
	global_store_dwordx4 v[10:11], v[2:5], off offset:16
	s_nop 1
	v_cvt_pk_bf16_f32 v2, v35, v39
	v_cvt_pk_bf16_f32 v3, v43, v47
	v_cvt_pk_bf16_f32 v4, v51, v55
	v_cvt_pk_bf16_f32 v5, v59, v63
	global_store_dwordx4 v[10:11], v[2:5], off offset:2064
	s_nop 1
	v_cvt_pk_bf16_f32 v2, v36, v40
	v_cvt_pk_bf16_f32 v3, v44, v48
	v_cvt_pk_bf16_f32 v4, v52, v56
	v_cvt_pk_bf16_f32 v5, v60, v64
	global_store_dwordx4 v[6:7], v[2:5], off offset:16
	s_nop 1
	v_cvt_pk_bf16_f32 v2, v37, v41
	v_cvt_pk_bf16_f32 v3, v45, v49
	v_cvt_pk_bf16_f32 v4, v53, v57
	v_cvt_pk_bf16_f32 v5, v61, v65
	global_store_dwordx4 v[6:7], v[70:73], off offset:2048
	global_store_dwordx4 v[6:7], v[2:5], off offset:2064
	s_branch .LBB0_16
